# combo8: combo7 with barrier waiters polling the top arrival counter directly (one atomic hop fewer)
# speedup vs baseline: 1.0327x; 1.0081x over previous
; __device__ __forceinline__ unsigned xb_ld(unsigned* p)              { return __hip_atomic_load(p, __ATOMIC_RELAXED, __HIP_MEMORY_SCOPE_AGENT); }
; __device__ __forceinline__ unsigned xb_add(unsigned* p, unsigned v) { return __hip_atomic_fetch_add(p, v, __ATOMIC_RELAXED, __HIP_MEMORY_SCOPE_AGENT); }
; #define XB_SPIN(cond, bar) do { unsigned _sp = 0; while (cond) { __builtin_amdgcn_s_sleep(1); \
;     if ((++_sp & 255u) == 0u) { if (xb_ld(&(bar)[XB_TMO])) break; if (_sp > XB_SPIN_CAP) { atomicAdd(&(bar)[XB_TMO], 1u); break; } } } } while (0)
; __device__ __forceinline__ void xcd_barrier(const XcdBarrier& b) {
;     ...
;         const unsigned old = xb_add(&bar[XB_XSUB(b.x)], 1u);
;         const unsigned gen = old / nloc;
;         if (old + 1u == (gen + 1u) * nloc) {
;             __builtin_amdgcn_fence(__ATOMIC_RELEASE, "agent");
;             asm volatile("s_waitcnt vmcnt(0)" ::: "memory");
;             const unsigned og = xb_add(&bar[XB_TOP], 1u);
;             const unsigned tg = og / nx;
;             if (og + 1u == (tg + 1u) * nx) xb_add(&bar[XB_TOPGEN], 1u);
;             else XB_SPIN(xb_ld(&bar[XB_TOPGEN]) == tg, bar);
;             __builtin_amdgcn_fence(__ATOMIC_ACQUIRE, "agent");
;             xb_add(&bar[XB_XGEN(b.x)], 1u);
;             asm volatile("s_waitcnt vmcnt(0)" ::: "memory");
;         } else {
;             XB_SPIN(xb_ld(&bar[XB_XGEN(b.x)]) == gen, bar);
;             __builtin_amdgcn_fence(__ATOMIC_ACQUIRE, "agent");
;             asm volatile("s_waitcnt vmcnt(0)" ::: "memory");
.LBB0_92:
	s_or_b64 exec, exec, s[6:7]
	v_cvt_f32_u32_e32 v4, v2
	s_waitcnt vmcnt(0)
	v_readfirstlane_b32 s4, v3
	v_sub_u32_e32 v3, 0, v2
	v_rcp_iflag_f32_e32 v4, v4
	v_add_u32_e32 v5, s4, v1
	v_mul_f32_e32 v4, 0x4f7ffffe, v4
	v_cvt_u32_f32_e32 v4, v4
	v_mul_lo_u32 v1, v3, v4
	v_mul_hi_u32 v1, v4, v1
	v_add_u32_e32 v1, v4, v1
	v_mul_hi_u32 v1, v5, v1
	v_mul_lo_u32 v3, v1, v2
	v_sub_u32_e32 v3, v5, v3
	v_add_u32_e32 v4, 1, v1
	v_cmp_ge_u32_e32 vcc, v3, v2
	s_nop 1
	v_cndmask_b32_e32 v1, v1, v4, vcc
	v_sub_u32_e32 v4, v3, v2
	v_cndmask_b32_e32 v3, v3, v4, vcc
	v_add_u32_e32 v4, 1, v1
	v_cmp_ge_u32_e32 vcc, v3, v2
	v_add_u32_e32 v3, 1, v5
	s_nop 0
	v_cndmask_b32_e32 v1, v1, v4, vcc
	v_mul_lo_u32 v4, v2, v1
	v_add_u32_e32 v2, v4, v2
	v_cmp_ne_u32_e32 vcc, v3, v2
	s_and_saveexec_b64 s[4:5], vcc
	s_xor_b64 s[4:5], exec, s[4:5]
	s_cbranch_execz .LBB0_106
	s_waitcnt lgkmcnt(0)
	buffer_inv sc1
	v_mad_u32_u24 v210, v1, v0, v0
	v_mov_b32_e32 v0, 0
	s_add_u32 s10, s68, 0xd6b0400
	s_addc_u32 s11, s69, 0
	s_nop 0
	global_load_dword v0, v0, s[10:11] sc1
	s_waitcnt vmcnt(0)
	v_cmp_lt_u32_e32 vcc, v0, v210
	s_and_saveexec_b64 s[6:7], vcc
	s_cbranch_execz .LBB0_105
	s_add_u32 s8, s68, 0xd6ad200
	s_addc_u32 s9, s69, 0
	s_mov_b32 s22, 1
	s_mov_b64 s[12:13], 0
	v_mov_b32_e32 v0, 0
	s_branch .LBB0_96

; __device__ __forceinline__ unsigned xb_ld(unsigned* p)              { return __hip_atomic_load(p, __ATOMIC_RELAXED, __HIP_MEMORY_SCOPE_AGENT); }
; #define XB_SPIN(cond, bar) do { unsigned _sp = 0; while (cond) { __builtin_amdgcn_s_sleep(1); \
;     if ((++_sp & 255u) == 0u) { if (xb_ld(&(bar)[XB_TMO])) break; if (_sp > XB_SPIN_CAP) { atomicAdd(&(bar)[XB_TMO], 1u); break; } } } } while (0)
; __device__ __forceinline__ void xcd_barrier(const XcdBarrier& b) {
;     ...
;             XB_SPIN(xb_ld(&bar[XB_XGEN(b.x)]) == gen, bar);
.LBB0_100:
	global_load_dword v2, v0, s[10:11] sc1
	s_add_i32 s22, s22, 1
	s_mov_b64 s[18:19], -1
	s_waitcnt vmcnt(0)
	v_cmp_ge_u32_e32 vcc, v2, v210
	s_orn2_b64 s[16:17], vcc, exec
	s_branch .LBB0_95

; __device__ __forceinline__ unsigned xb_ld(unsigned* p)              { return __hip_atomic_load(p, __ATOMIC_RELAXED, __HIP_MEMORY_SCOPE_AGENT); }
; __device__ __forceinline__ unsigned xb_add(unsigned* p, unsigned v) { return __hip_atomic_fetch_add(p, v, __ATOMIC_RELAXED, __HIP_MEMORY_SCOPE_AGENT); }
; #define XB_SPIN(cond, bar) do { unsigned _sp = 0; while (cond) { __builtin_amdgcn_s_sleep(1); \
;     if ((++_sp & 255u) == 0u) { if (xb_ld(&(bar)[XB_TMO])) break; if (_sp > XB_SPIN_CAP) { atomicAdd(&(bar)[XB_TMO], 1u); break; } } } } while (0)
; __device__ __forceinline__ void xcd_barrier(const XcdBarrier& b) {
;     ...
;             asm volatile("s_waitcnt vmcnt(0)" ::: "memory");
;             const unsigned og = xb_add(&bar[XB_TOP], 1u);
;             const unsigned tg = og / nx;
;             if (og + 1u == (tg + 1u) * nx) xb_add(&bar[XB_TOPGEN], 1u);
;             else XB_SPIN(xb_ld(&bar[XB_TOPGEN]) == tg, bar);
.LBB0_109:
	s_or_b64 exec, exec, s[6:7]
	v_cvt_f32_u32_e32 v3, v0
	s_waitcnt vmcnt(0)
	v_readfirstlane_b32 s4, v2
	s_add_u32 s6, s68, 0xd6b0500
	s_addc_u32 s7, s69, 0
	s_add_u32 s100, s68, 0xd6b0400
	s_addc_u32 s101, s69, 0
	v_rcp_iflag_f32_e32 v3, v3
	v_add_u32_e32 v1, s4, v1
	v_add_u32_e32 v4, 1, v1
	s_mov_b64 s[8:9], -1
	v_mul_f32_e32 v2, 0x4f7ffffe, v3
	v_cvt_u32_f32_e32 v2, v2
	v_sub_u32_e32 v3, 0, v0
	v_mul_lo_u32 v3, v3, v2
	v_mul_hi_u32 v3, v2, v3
	v_add_u32_e32 v2, v2, v3
	v_mul_hi_u32 v2, v1, v2
	v_mul_lo_u32 v3, v2, v0
	v_sub_u32_e32 v1, v1, v3
	v_add_u32_e32 v5, 1, v2
	v_cmp_ge_u32_e32 vcc, v1, v0
	v_sub_u32_e32 v3, v1, v0
	s_nop 0
	v_cndmask_b32_e32 v2, v2, v5, vcc
	v_cndmask_b32_e32 v1, v1, v3, vcc
	v_add_u32_e32 v3, 1, v2
	v_cmp_ge_u32_e32 vcc, v1, v0
	s_nop 1
	v_cndmask_b32_e32 v2, v2, v3, vcc
	v_mul_lo_u32 v1, v0, v2
	v_add_u32_e32 v0, v1, v0
	v_mov_b32_e32 v210, v0
	v_cmp_ne_u32_e32 vcc, v4, v0
	v_mov_b64_e32 v[0:1], s[6:7]
	s_and_saveexec_b64 s[4:5], vcc
	s_cbranch_execz .LBB0_121
	v_mov_b32_e32 v0, 0
	global_load_dword v1, v0, s[100:101] sc1
	s_mov_b64 s[12:13], 0
	s_waitcnt vmcnt(0)
	v_cmp_lt_u32_e32 vcc, v1, v210
	s_and_saveexec_b64 s[10:11], vcc
	s_cbranch_execz .LBB0_120
	s_add_u32 s8, s68, 0xd6ad200
	s_addc_u32 s9, s69, 0
	s_mov_b32 s22, 1
	s_branch .LBB0_113

; __device__ __forceinline__ unsigned xb_ld(unsigned* p)              { return __hip_atomic_load(p, __ATOMIC_RELAXED, __HIP_MEMORY_SCOPE_AGENT); }
; #define XB_SPIN(cond, bar) do { unsigned _sp = 0; while (cond) { __builtin_amdgcn_s_sleep(1); \
;     if ((++_sp & 255u) == 0u) { if (xb_ld(&(bar)[XB_TMO])) break; if (_sp > XB_SPIN_CAP) { atomicAdd(&(bar)[XB_TMO], 1u); break; } } } } while (0)
; __device__ __forceinline__ void xcd_barrier(const XcdBarrier& b) {
;     ...
;             else XB_SPIN(xb_ld(&bar[XB_TOPGEN]) == tg, bar);
.LBB0_117:
	global_load_dword v1, v0, s[100:101] sc1
	s_add_i32 s22, s22, 1
	s_mov_b64 s[16:17], -1
	s_waitcnt vmcnt(0)
	v_cmp_ge_u32_e32 vcc, v1, v210
	s_orn2_b64 s[20:21], vcc, exec
	s_branch .LBB0_112

; __global__ void __launch_bounds__(512, 2) mega(Params P) {
	.amdhsa_kernel _Z4mega6Params
		.amdhsa_group_segment_fixed_size 0
		.amdhsa_private_segment_fixed_size 0
		.amdhsa_kernarg_size 416
		.amdhsa_user_sgpr_count 2
		.amdhsa_user_sgpr_dispatch_ptr 0
		.amdhsa_user_sgpr_queue_ptr 0
		.amdhsa_user_sgpr_kernarg_segment_ptr 1
		.amdhsa_user_sgpr_dispatch_id 0
		.amdhsa_user_sgpr_kernarg_preload_length 0
		.amdhsa_user_sgpr_kernarg_preload_offset 0
		.amdhsa_user_sgpr_private_segment_size 0
		.amdhsa_uses_dynamic_stack 0
		.amdhsa_enable_private_segment 0
		.amdhsa_system_sgpr_workgroup_id_x 1
		.amdhsa_system_sgpr_workgroup_id_y 0
		.amdhsa_system_sgpr_workgroup_id_z 0
		.amdhsa_system_sgpr_workgroup_info 0
		.amdhsa_system_vgpr_workitem_id 2
		.amdhsa_next_free_vgpr 255
		.amdhsa_next_free_sgpr 102
		.amdhsa_accum_offset 256
		.amdhsa_reserve_vcc 1
		.amdhsa_float_round_mode_32 0
		.amdhsa_float_round_mode_16_64 0
		.amdhsa_float_denorm_mode_32 3
		.amdhsa_float_denorm_mode_16_64 3
		.amdhsa_dx10_clamp 1
		.amdhsa_ieee_mode 1
		.amdhsa_fp16_overflow 0
		.amdhsa_tg_split 0
		.amdhsa_exception_fp_ieee_invalid_op 0
		.amdhsa_exception_fp_denorm_src 0
		.amdhsa_exception_fp_ieee_div_zero 0
		.amdhsa_exception_fp_ieee_overflow 0
		.amdhsa_exception_fp_ieee_underflow 0
		.amdhsa_exception_fp_ieee_inexact 0
		.amdhsa_exception_int_div_zero 0
	.end_amdhsa_kernel

; __global__ void __launch_bounds__(512, 2) mega(Params P) {
.Lfunc_end0:
	.size	_Z4mega6Params, .Lfunc_end0-_Z4mega6Params
	.set _Z4mega6Params.num_vgpr, 255
	.set _Z4mega6Params.num_agpr, 0
	.set _Z4mega6Params.numbered_sgpr, 102
	.set _Z4mega6Params.num_named_barrier, 0
	.set _Z4mega6Params.private_seg_size, 0
	.set _Z4mega6Params.uses_vcc, 1
	.set _Z4mega6Params.uses_flat_scratch, 0
	.set _Z4mega6Params.has_dyn_sized_stack, 0
	.set _Z4mega6Params.has_recursion, 0
	.set _Z4mega6Params.has_indirect_call, 0

; __global__ void __launch_bounds__(512, 2) mega(Params P) {
amdhsa.kernels:
  - .agpr_count:     0
    .args:
      - .offset:         0
        .size:           160
        .value_kind:     by_value
      - .offset:         160
        .size:           4
        .value_kind:     hidden_block_count_x
      - .offset:         164
        .size:           4
        .value_kind:     hidden_block_count_y
      - .offset:         168
        .size:           4
        .value_kind:     hidden_block_count_z
      - .offset:         172
        .size:           2
        .value_kind:     hidden_group_size_x
      - .offset:         174
        .size:           2
        .value_kind:     hidden_group_size_y
      - .offset:         176
        .size:           2
        .value_kind:     hidden_group_size_z
      - .offset:         178
        .size:           2
        .value_kind:     hidden_remainder_x
      - .offset:         180
        .size:           2
        .value_kind:     hidden_remainder_y
      - .offset:         182
        .size:           2
        .value_kind:     hidden_remainder_z
      - .offset:         200
        .size:           8
        .value_kind:     hidden_global_offset_x
      - .offset:         208
        .size:           8
        .value_kind:     hidden_global_offset_y
      - .offset:         216
        .size:           8
        .value_kind:     hidden_global_offset_z
      - .offset:         224
        .size:           2
        .value_kind:     hidden_grid_dims
      - .offset:         248
        .size:           8
        .value_kind:     hidden_multigrid_sync_arg
      - .offset:         280
        .size:           4
        .value_kind:     hidden_dynamic_lds_size
    .group_segment_fixed_size: 0
    .kernarg_segment_align: 8
    .kernarg_segment_size: 416
    .language:       OpenCL C
    .language_version:
      - 2
      - 0
    .max_flat_workgroup_size: 512
    .name:           _Z4mega6Params
    .private_segment_fixed_size: 0
    .sgpr_count:     108
    .sgpr_spill_count: 63
    .symbol:         _Z4mega6Params.kd
    .uniform_work_group_size: 1
    .uses_dynamic_stack: false
    .vgpr_count:     255
    .vgpr_spill_count: 0
    .wavefront_size: 64
